# attention unit start: wait only for the K/V tile loads before the LDS write, Q fragment loads waited at the first QK MFMA
# speedup vs baseline: 1.0005x; 1.0005x over previous
; #define AT_BAR() do { asm volatile("s_waitcnt lgkmcnt(0)" ::: "memory"); __builtin_amdgcn_s_barrier(); asm volatile("" ::: "memory"); } while (0)
; #define AT_GLOAD(kt) do { ka = *(const u32x4*)(kg0 + (size_t)(kt) * 128 * 768); kb = *(const u32x4*)(kg1 + (size_t)(kt) * 128 * 768); kc = *(const u32x4*)(kg2 + (size_t)(kt) * 128 * 768); \
;         va = *(const u32x4*)(vg0 + (kt) * 128); vb = *(const u32x4*)(vg1 + (kt) * 128); } while (0)
; __device__ __forceinline__ void phase_attn(CParams& P, LAS unsigned char* lds) {
;     ...
;         const int sh = u >> 4, qb = u & 15, s = sh >> 3, h = sh & 7; const size_t tok0 = (size_t)s * SEQ;
;         bf16x8 qf[6]; { const bf16_t* qp = Q + (tok0 + qb * 256 + wid * 32 + ql) * 768 + h * 96 + 8 * hi;
; #pragma unroll
;             for (int ds = 0; ds < 6; ++ds) qf[ds] = *(const bf16x8*)(qp + 16 * ds); }
;         const bf16_t* kg0 = KF + (tok0 + kr0) * 768 + h * 96 + kc0 * 8; const bf16_t* kg1 = KF + (tok0 + kr1) * 768 + h * 96 + kc1 * 8; const bf16_t* kg2 = KF + (tok0 + kr2) * 768 + h * 96 + kc2 * 8;
;         const bf16_t* vg0 = VT + ((size_t)(s * 8 + h) * 64 + vr0) * SEQ + vc0 * 8; const bf16_t* vg1 = vg0 + (size_t)32 * SEQ;
;         u32x4 ka, kb, kc, va, vb;
;         f32x16 o0 = {}, o1 = {}, pA0, pA1; float mrun = 0.f, lrun = 0.f; bf16x8 pf[4], kfa[6], kfb[6], vfa[4], vfb[4];
;         AT_GLOAD(0); AT_LWRITE(0);
;         AT_BAR();
.LBB0_612:
	s_ashr_i32 s4, s11, 7
	s_ashr_i32 s5, s4, 31
	s_lshl_b64 s[6:7], s[4:5], 12
	s_lshl_b32 s5, s11, 8
	s_and_b32 s5, s5, 0xf00
	s_or_b32 s8, s6, s5
	s_mov_b32 s9, s7
	s_movk_i32 s13, 0x600
	v_lshl_add_u64 v[4:5], s[6:7], 0, v[162:163]
	v_mov_b64_e32 v[6:7], s[42:43]
	s_bfe_u32 s12, s11, 0x30004
	v_lshl_add_u64 v[184:185], s[8:9], 0, v[164:165]
	v_mad_u64_u32 v[8:9], s[8:9], v4, s13, v[6:7]
	s_mul_i32 s28, s12, 0xc0
	v_mad_i32_i24 v9, v5, s13, v9
	v_lshl_add_u64 v[4:5], v[8:9], 0, s[28:29]
	v_lshl_add_u64 v[8:9], s[6:7], 0, v[160:161]
	v_mad_u64_u32 v[10:11], s[8:9], v8, s13, v[6:7]
	v_mad_i32_i24 v11, v9, s13, v11
	v_lshl_add_u64 v[8:9], v[10:11], 0, s[28:29]
	v_lshl_add_u64 v[10:11], s[6:7], 0, v[158:159]
	v_mov_b64_e32 v[0:1], s[40:41]
	v_mad_u64_u32 v[6:7], s[6:7], v10, s13, v[6:7]
	s_lshl_b32 s5, s4, 3
	v_mad_u64_u32 v[0:1], s[8:9], v184, s13, v[0:1]
	s_or_b32 s6, s5, s12
	v_mov_b32_e32 v2, v1
	s_ashr_i32 s7, s6, 31
	v_mad_i32_i24 v7, v11, s13, v7
	s_lshl_b64 s[6:7], s[6:7], 19
	v_mad_u64_u32 v[2:3], s[8:9], v185, s13, v[2:3]
	v_lshl_add_u64 v[4:5], v[166:167], 1, v[4:5]
	v_lshl_add_u64 v[6:7], v[6:7], 0, s[28:29]
	v_lshl_add_u64 v[10:11], v[172:173], 0, s[6:7]
	s_mov_b32 s5, 0x40000
	v_mov_b32_e32 v1, v2
	v_lshl_add_u64 v[8:9], v[168:169], 1, v[8:9]
	v_lshl_add_u64 v[6:7], v[170:171], 1, v[6:7]
	global_load_dwordx4 v[66:69], v[4:5], off
	global_load_dwordx4 v[70:73], v[8:9], off
	global_load_dwordx4 v[74:77], v[6:7], off
	global_load_dwordx4 v[98:101], v[10:11], off
	v_add_co_u32_e32 v4, vcc, s5, v10
	v_lshl_add_u64 v[0:1], v[0:1], 0, s[28:29]
	s_nop 0
	v_addc_co_u32_e32 v5, vcc, 0, v11, vcc
	v_lshl_add_u64 v[0:1], v[0:1], 0, v[64:65]
	global_load_dwordx4 v[106:109], v[4:5], off
	global_load_dwordx4 v[78:81], v[0:1], off
	global_load_dwordx4 v[82:85], v[0:1], off offset:32
	global_load_dwordx4 v[86:89], v[0:1], off offset:64
	global_load_dwordx4 v[90:93], v[0:1], off offset:96
	global_load_dwordx4 v[94:97], v[0:1], off offset:128
	global_load_dwordx4 v[102:105], v[0:1], off offset:160
	v_add_u32_e32 v14, 0xd000, v208
	v_add_u32_e32 v15, 0xf000, v208
	s_mul_hi_i32 s5, s4, 0x600000
	s_mul_i32 s4, s4, 0x600000
	v_mov_b32_e32 v0, v65
	v_mov_b32_e32 v1, v65
	v_mov_b32_e32 v2, v65
	v_mov_b32_e32 v3, v65
	v_mov_b32_e32 v4, v65
	v_mov_b32_e32 v5, v65
	v_mov_b32_e32 v6, v65
	v_mov_b32_e32 v7, v65
	v_mov_b32_e32 v8, v65
	v_mov_b32_e32 v9, v65
	v_mov_b32_e32 v10, v65
	v_mov_b32_e32 v11, v65
	v_mov_b32_e32 v12, v65
	v_mov_b32_e32 v13, v65
	s_or_b32 s4, s4, s28
	s_mov_b32 s13, 0
	v_lshl_add_u64 v[186:187], v[176:177], 0, s[4:5]
	v_lshl_add_u64 v[188:189], v[178:179], 0, s[4:5]
	v_lshl_add_u64 v[190:191], v[180:181], 0, s[4:5]
	v_lshl_add_u64 v[192:193], v[174:175], 0, s[6:7]
	v_mov_b32_e32 v194, 0
	s_mov_b64 s[46:47], 0
	v_mov_b32_e32 v183, 0
	s_waitcnt vmcnt(6)
	ds_write_b128 v205, v[66:69]
	ds_write_b128 v206, v[70:73]
	ds_write_b128 v207, v[74:77]
	ds_write2_b64 v14, v[98:99], v[100:101] offset1:2
	ds_write2_b64 v15, v[106:107], v[108:109] offset0:64 offset1:66
	s_waitcnt lgkmcnt(0)
	s_barrier
	v_mov_b32_e32 v14, v65
	v_mov_b32_e32 v15, v65
	v_mov_b64_e32 v[30:31], v[14:15]
	v_mov_b64_e32 v[28:29], v[12:13]
	v_mov_b64_e32 v[26:27], v[10:11]
	v_mov_b64_e32 v[24:25], v[8:9]
	v_mov_b64_e32 v[22:23], v[6:7]
	v_mov_b64_e32 v[20:21], v[4:5]
	v_mov_b64_e32 v[18:19], v[2:3]
	v_mov_b64_e32 v[16:17], v[0:1]
	s_branch .LBB0_614

; #define AT_GLOAD(kt) do { ka = *(const u32x4*)(kg0 + (size_t)(kt) * 128 * 768); kb = *(const u32x4*)(kg1 + (size_t)(kt) * 128 * 768); kc = *(const u32x4*)(kg2 + (size_t)(kt) * 128 * 768); \
;         va = *(const u32x4*)(vg0 + (kt) * 128); vb = *(const u32x4*)(vg1 + (kt) * 128); } while (0)
; #define AT_KFRAG(buf, sub) do { const LAS unsigned char* kb_ = lds + (buf) * KBUF + ((sub) * 64 + ql) * KROW + hi * 16; _Pragma("unroll") for (int ds = 0; ds < 6; ++ds) { \
;         kfa[ds] = *(const LAS bf16x8*)(kb_ + ds * 32); kfb[ds] = *(const LAS bf16x8*)(kb_ + 32 * KROW + ds * 32); } } while (0)
; #define AT_QK(S) do { const f32x16 zz = {}; S##0 = MFMA32(kfa[0], qf[0], zz); S##1 = MFMA32(kfb[0], qf[0], zz); _Pragma("unroll") for (int ds = 1; ds < 6; ++ds) { \
;         S##0 = MFMA32(kfa[ds], qf[ds], S##0); S##1 = MFMA32(kfb[ds], qf[ds], S##1); } } while (0)
; #define AT_VFRAG(buf, sub) do { const LAS unsigned char* vb_ = lds + VOFF + (buf) * VBUF + ql * VROW + (sub) * 128 + hi * 16; _Pragma("unroll") for (int ks = 0; ks < 4; ++ks) { \
;         vfa[ks] = *(const LAS bf16x8*)(vb_ + ks * 32); vfb[ks] = *(const LAS bf16x8*)(vb_ + 32 * VROW + ks * 32); } } while (0)
; #define AT_PV() do { _Pragma("unroll") for (int ks = 0; ks < 4; ++ks) { o0 = MFMA32(vfa[ks], pf[ks], o0); o1 = MFMA32(vfb[ks], pf[ks], o1); } } while (0)
; __device__ __forceinline__ void phase_attn(CParams& P, LAS unsigned char* lds) {
;     ...
;         for (int kt = 0; kt < NT; ++kt) { const int cur = kt & 1;
;             if (kt + 1 < NT) AT_GLOAD(kt + 1);
;             AT_KFRAG(cur, 0);
;             AT_QK(pA); AT_VFRAG(cur, 0); AT_SM(pA, pA, false, kt == 0); AT_KFRAG(cur, 1); AT_PV();
.LBB0_616:
	s_and_b32 s14, s13, 1
	s_mul_i32 s4, s14, 0x6800
	v_add_u32_e32 v142, s4, v203
	ds_read_b128 v[32:35], v142
	ds_read_b128 v[110:113], v142 offset:32
	s_mul_i32 s4, s14, 0x4400
	v_add_u32_e32 v209, s4, v204
	s_cmp_eq_u32 s46, 0
	s_waitcnt vmcnt(5)
	s_waitcnt lgkmcnt(1)
	v_mfma_f32_32x32x16_bf16 v[48:63], v[32:35], v[78:81], 0
	ds_read_b128 v[32:35], v142 offset:6656
	ds_read_b128 v[114:117], v142 offset:6688
	s_mov_b32 s8, 0xc1000000
	s_cselect_b64 s[4:5], -1, 0
	s_waitcnt lgkmcnt(1)
	v_mfma_f32_32x32x16_bf16 v[32:47], v[32:35], v[78:81], 0
	v_mfma_f32_32x32x16_bf16 v[48:63], v[110:113], v[82:85], v[48:63]
	s_waitcnt lgkmcnt(0)
	v_mfma_f32_32x32x16_bf16 v[32:47], v[114:117], v[82:85], v[32:47]
	ds_read_b128 v[110:113], v142 offset:64
	ds_read_b128 v[114:117], v142 offset:96
	s_waitcnt lgkmcnt(1)
	v_mfma_f32_32x32x16_bf16 v[48:63], v[110:113], v[86:89], v[48:63]
	ds_read_b128 v[110:113], v142 offset:6720
	ds_read_b128 v[118:121], v142 offset:6752
	s_waitcnt lgkmcnt(1)
	v_mfma_f32_32x32x16_bf16 v[32:47], v[110:113], v[86:89], v[32:47]
	v_mfma_f32_32x32x16_bf16 v[48:63], v[114:117], v[90:93], v[48:63]
	ds_read_b128 v[110:113], v142 offset:128
	ds_read_b128 v[114:117], v142 offset:160
	s_waitcnt lgkmcnt(2)
	v_mfma_f32_32x32x16_bf16 v[32:47], v[118:121], v[90:93], v[32:47]
	s_waitcnt lgkmcnt(1)
	v_mfma_f32_32x32x16_bf16 v[48:63], v[110:113], v[94:97], v[48:63]
	ds_read_b128 v[110:113], v142 offset:6784
	ds_read_b128 v[144:147], v142 offset:6816
	ds_read_b128 v[122:125], v209 offset:53248
	ds_read_b128 v[118:121], v209 offset:53280
	ds_read_b128 v[138:141], v209 offset:61952
	ds_read_b128 v[134:137], v209 offset:61984
	s_waitcnt lgkmcnt(5)
	v_mfma_f32_32x32x16_bf16 v[32:47], v[110:113], v[94:97], v[32:47]
	v_mfma_f32_32x32x16_bf16 v[48:63], v[114:117], v[102:105], v[48:63]
	ds_read_b128 v[114:117], v209 offset:53312
	ds_read_b128 v[110:113], v209 offset:53344
	ds_read_b128 v[130:133], v209 offset:62016
	ds_read_b128 v[126:129], v209 offset:62048
	s_waitcnt lgkmcnt(8)
	v_mfma_f32_32x32x16_bf16 v[32:47], v[144:147], v[102:105], v[32:47]
	s_nop 5
	v_max_f32_e32 v143, v49, v49
	v_max_f32_e32 v148, v48, v48
	v_max_f32_e32 v143, v148, v143
	s_nop 2
	v_max3_f32 v144, v50, v51, v33
	v_max3_f32 v143, v143, v32, v34
	v_max3_f32 v143, v143, v35, v52
	v_max3_f32 v144, v144, v54, v55
	v_max3_f32 v143, v143, v53, v36
	v_max3_f32 v144, v144, v38, v39
	v_max3_f32 v143, v143, v37, v56
	v_max3_f32 v144, v144, v58, v59
	v_max3_f32 v143, v143, v57, v40
	v_max3_f32 v144, v144, v42, v43
	v_max3_f32 v143, v143, v41, v60
	v_max3_f32 v144, v144, v62, v63
	v_max3_f32 v143, v143, v61, v44
	v_max3_f32 v144, v144, v46, v47
	v_max3_f32 v143, v143, v45, v144
	v_mov_b32_e32 v144, v143
	s_nop 1
	v_permlane32_swap_b32_e32 v143, v144
	v_max_f32_e32 v144, v144, v144
	v_max_f32_e32 v143, v143, v143
	v_max_f32_e32 v143, v143, v144
	v_sub_f32_e32 v143, v143, v194
	v_cmp_gt_f32_e64 s[8:9], s8, v143
	v_cmp_lt_f32_e64 s[6:7], s96, v143
	s_and_b64 s[18:19], s[4:5], s[8:9]
	s_or_b64 vcc, s[6:7], s[18:19]
	s_cbranch_vccz .LBB0_618
	s_or_b64 vcc, s[6:7], s[8:9]
	v_cndmask_b32_e32 v144, 0, v143, vcc
	v_max_f32_e32 v143, v143, v143
	v_max_f32_e32 v143, 0, v143
	v_cndmask_b32_e64 v143, v143, v144, s[4:5]
	v_exp_f32_e64 v144, -v143
	v_add_f32_e32 v194, v194, v143
	v_cndmask_b32_e64 v144, v144, 0, s[4:5]
	v_pk_mul_f32 v[14:15], v[14:15], v[144:145] op_sel_hi:[1,0]
	v_pk_mul_f32 v[12:13], v[12:13], v[144:145] op_sel_hi:[1,0]
	v_pk_mul_f32 v[10:11], v[10:11], v[144:145] op_sel_hi:[1,0]
	v_pk_mul_f32 v[8:9], v[8:9], v[144:145] op_sel_hi:[1,0]
	v_pk_mul_f32 v[6:7], v[6:7], v[144:145] op_sel_hi:[1,0]
	v_pk_mul_f32 v[4:5], v[4:5], v[144:145] op_sel_hi:[1,0]
	v_pk_mul_f32 v[2:3], v[2:3], v[144:145] op_sel_hi:[1,0]
	v_pk_mul_f32 v[0:1], v[0:1], v[144:145] op_sel_hi:[1,0]
	v_pk_mul_f32 v[30:31], v[30:31], v[144:145] op_sel_hi:[1,0]
	v_pk_mul_f32 v[28:29], v[28:29], v[144:145] op_sel_hi:[1,0]
	v_pk_mul_f32 v[26:27], v[26:27], v[144:145] op_sel_hi:[1,0]
	v_pk_mul_f32 v[24:25], v[24:25], v[144:145] op_sel_hi:[1,0]
	v_pk_mul_f32 v[22:23], v[22:23], v[144:145] op_sel_hi:[1,0]
	v_pk_mul_f32 v[20:21], v[20:21], v[144:145] op_sel_hi:[1,0]
	v_pk_mul_f32 v[18:19], v[18:19], v[144:145] op_sel_hi:[1,0]
	v_pk_mul_f32 v[16:17], v[16:17], v[144:145] op_sel_hi:[1,0]
	v_mul_f32_e32 v183, v183, v144
